# further instruction-count trims in the diff-attention loop (persistent SGPR stage base, single vmcnt wait before the staging ds_writes in all three attention loops, bias index base only on the near-di
# baseline (speedup 1.0000x reference)
; DI void attn_diff_unit(const Params& p, int li, int b, int h, int qb, char* smem, bool pre, int nh, bool has_next) {
;     ...
;   constexpr int KR = 272, VR = 320;
;   constexpr int STG = 128 * KR + 128 * VR;
;   const int vbase = tr_base(lane, VR);
;   float* tab = (float*)(smem + 2 * STG);
;   const int rg = w & 3, map = w >> 2;
;   const int qpos = qb * 128 + rg * 32 + r32;
;   const int qrow = b * S_ + qpos;
;   __syncthreads();
;   const float* t5t = (const float*)(p.ws + TB_T5) + h * 512;
;   if (tid < 512) tab[tid] = t5t[tid];
;   const float cL = t5t[0], cR = t5t[510];
;   bf16x8 qf[4];
; #pragma unroll
;   for (int s = 0; s < 4; ++s) qf[s] = *(const bf16x8*)(qd + (size_t)qrow * 1024 + h * 128 + map * 64 + s * 16 + hh * 8);
;   f32x16 O[4];
; #pragma unroll
;   for (int j = 0; j < 4; ++j)
; #pragma unroll
;     for (int i = 0; i < 16; ++i) O[j][i] = 0.f;
;   float m = 0.f, l = 0.f;
;   const int krow = tid >> 4, kpart = tid & 15;
;   const u16* gk = kd + (size_t)(b * S_ + krow) * 1024 + h * 128 + kpart * 8;
;   const u16* gv = vT + (size_t)(b * S_ + krow) * 1024 + h * 128 + kpart * 8;
;   u32x4 rk[4], rv[4];
;   if (!pre) {
; #pragma unroll
;     for (int i = 0; i < 4; ++i) { rk[i] = *(const u32x4*)(gk + (size_t)i * 32 * 1024); rv[i] = *(const u32x4*)(gv + (size_t)i * 32 * 1024); }
;   }
;   auto put_stage = [&](char* kb) {
;     char* vb = kb + 128 * KR;
; #pragma unroll
;     for (int i = 0; i < 4; ++i) {
;       *(u32x4*)(kb + (krow + 32 * i) * KR + kpart * 16) = rk[i];
;       *(u32x4*)(vb + (krow + 32 * i) * VR + kpart * 16) = rv[i];
;     }
;   };
;   auto get_stage = [&](int st) {
;     const int k0 = st * 128;
; #pragma unroll
;     for (int i = 0; i < 4; ++i) { rk[i] = *(const u32x4*)(gk + (size_t)(k0 + i * 32) * 1024); rv[i] = *(const u32x4*)(gv + (size_t)(k0 + i * 32) * 1024); }
;   };
;   if (!pre) put_stage(smem);
;   __syncthreads();
;   get_stage(1);
.LBB0_567:
	v_bfe_u32 v4, v146, 2, 2
	v_lshrrev_b32_e32 v5, 3, v146
	v_and_or_b32 v4, v5, 4, v4
	s_mov_b32 s3, 0x40000
	v_mul_u32_u24_e32 v163, 0x140, v4
	v_add_co_u32_e32 v4, vcc, s3, v148
	s_waitcnt lgkmcnt(0)
	s_nop 0
	v_addc_co_u32_e32 v5, vcc, 0, v149, vcc
	v_add_co_u32_e32 v6, vcc, s3, v150
	s_mov_b32 s3, 0x50000
	s_nop 0
	v_addc_co_u32_e32 v7, vcc, 0, v151, vcc
	s_barrier
	global_load_dwordx4 v[116:119], v[4:5], off
	global_load_dwordx4 v[128:131], v[6:7], off
	v_add_co_u32_e32 v4, vcc, s3, v148
	s_and_b32 s35, s39, 0xf80
	s_nop 0
	v_addc_co_u32_e32 v5, vcc, 0, v149, vcc
	v_add_co_u32_e32 v6, vcc, s3, v150
	s_mov_b32 s3, 0x60000
	s_nop 0
	v_addc_co_u32_e32 v7, vcc, 0, v151, vcc
	global_load_dwordx4 v[112:115], v[4:5], off
	global_load_dwordx4 v[120:123], v[6:7], off
	v_add_co_u32_e32 v4, vcc, s3, v148
	s_add_i32 s40, s40, s89
	s_nop 0
	v_addc_co_u32_e32 v5, vcc, 0, v149, vcc
	v_add_co_u32_e32 v6, vcc, s3, v150
	s_mov_b32 s3, 0x70000
	s_nop 0
	v_addc_co_u32_e32 v7, vcc, 0, v151, vcc
	global_load_dwordx4 v[124:127], v[4:5], off
	global_load_dwordx4 v[132:135], v[6:7], off
	v_add_co_u32_e32 v4, vcc, s3, v148
	s_sub_i32 s42, 0, s35
	s_nop 0
	v_addc_co_u32_e32 v5, vcc, 0, v149, vcc
	v_add_co_u32_e32 v6, vcc, s3, v150
	s_lshr_b32 s2, s40, 5
	s_nop 0
	v_addc_co_u32_e32 v7, vcc, 0, v151, vcc
	global_load_dwordx4 v[136:139], v[4:5], off
	global_load_dwordx4 v[140:143], v[6:7], off
	v_and_b32_e32 v158, 63, v146
	s_cmpk_lt_u32 s40, 0x100
	v_lshlrev_b32_e32 v144, 10, v3
	s_cselect_b64 s[28:29], -1, 0
	s_cmpk_gt_u32 s40, 0xff
	v_and_b32_e32 v3, 16, v146
	v_lshlrev_b32_e32 v162, 2, v158
	s_cselect_b64 s[22:23], -1, 0
	v_and_or_b32 v3, v162, 12, v3
	s_sub_i32 s2, s2, s34
	v_lshlrev_b32_e32 v164, 1, v3
	v_lshlrev_b32_e32 v3, 7, v155
	v_add_u32_e32 v166, 0, v160
	s_lshl_b32 s2, s2, 7
	v_or_b32_e32 v1, s35, v1
	v_lshl_or_b32 v165, v2, 4, v3
	v_lshlrev_b32_e32 v153, 2, v2
	v_add_u32_e32 v2, 0, v161
	v_add_u32_e32 v3, 0x8800, v166
	s_ashr_i32 s3, s2, 31
	v_mul_u32_u24_e32 v167, 0x110, v0
	v_add_u32_e32 v0, v1, v0
	v_mov_b32_e32 v169, 0
	s_mov_b32 s24, 0
	v_xor_b32_e32 v147, 0x80, v162
	v_sub_u32_e32 v168, v153, v0
	s_mov_b64 s[34:35], 0xb0000
	v_add_u32_e32 v170, v2, v159
	v_add_u32_e32 v171, v3, v159
	s_lshl_b64 s[36:37], s[2:3], 1
	s_mov_b32 s43, 0
	v_mov_b32_e32 v172, 0
	v_mov_b32_e32 v0, 0
	v_mov_b32_e32 v1, v169
	v_mov_b32_e32 v2, v169
	v_mov_b32_e32 v3, v169
	v_mov_b32_e32 v4, v169
	v_mov_b32_e32 v5, v169
	v_mov_b32_e32 v6, v169
	v_mov_b32_e32 v7, v169
	v_mov_b32_e32 v8, v169
	v_mov_b32_e32 v9, v169
	v_mov_b32_e32 v10, v169
	v_mov_b32_e32 v11, v169
	v_mov_b32_e32 v12, v169
	v_mov_b32_e32 v13, v169
	v_mov_b32_e32 v14, v169
	v_mov_b32_e32 v15, v169
	v_mov_b32_e32 v16, 0
	v_mov_b32_e32 v17, v169
	v_mov_b32_e32 v18, v169
	v_mov_b32_e32 v19, v169
	v_mov_b32_e32 v20, v169
	v_mov_b32_e32 v21, v169
	v_mov_b32_e32 v22, v169
	v_mov_b32_e32 v23, v169
	v_mov_b32_e32 v24, v169
	v_mov_b32_e32 v25, v169
	v_mov_b32_e32 v26, v169
	v_mov_b32_e32 v27, v169
	v_mov_b32_e32 v28, v169
	v_mov_b32_e32 v29, v169
	v_mov_b32_e32 v30, v169
	v_mov_b32_e32 v31, v169
	v_mov_b32_e32 v32, 0
	v_mov_b32_e32 v33, v169
	v_mov_b32_e32 v34, v169
	v_mov_b32_e32 v35, v169
	v_mov_b32_e32 v36, v169
	v_mov_b32_e32 v37, v169
	v_mov_b32_e32 v38, v169
	v_mov_b32_e32 v39, v169
	v_mov_b32_e32 v40, v169
	v_mov_b32_e32 v41, v169
	v_mov_b32_e32 v42, v169
	v_mov_b32_e32 v43, v169
	v_mov_b32_e32 v44, v169
	v_mov_b32_e32 v45, v169
	v_mov_b32_e32 v46, v169
	v_mov_b32_e32 v47, v169
	v_mov_b32_e32 v48, 0
	v_mov_b32_e32 v49, v169
	v_mov_b32_e32 v50, v169
	v_mov_b32_e32 v51, v169
	v_mov_b32_e32 v52, v169
	v_mov_b32_e32 v53, v169
	v_mov_b32_e32 v54, v169
	v_mov_b32_e32 v55, v169
	v_mov_b32_e32 v56, v169
	v_mov_b32_e32 v57, v169
	v_mov_b32_e32 v58, v169
	v_mov_b32_e32 v59, v169
	v_mov_b32_e32 v60, v169
	v_mov_b32_e32 v61, v169
	v_mov_b32_e32 v62, v169
	s_waitcnt vmcnt(8)
	s_mov_b32 s45, 0
	v_readfirstlane_b32 s100, v148
	s_nop 3
	v_subrev_u32_e32 v246, s100, v148
	v_add_u32_e32 v247, 0x10000, v246
	v_add_u32_e32 v248, 0x20000, v246
	v_add_u32_e32 v249, 0x30000, v246
	v_readfirstlane_b32 s101, v149
	v_add_u32_e32 v254, v167, v165
	s_nop 3
	s_add_u32 s100, s100, 0x80000
	s_addc_u32 s101, s101, 0
	v_mov_b32_e32 v63, v169
; DI f32x16 mfma32(bf16x8 a, bf16x8 b, f32x16 c) { return __builtin_amdgcn_mfma_f32_32x32x16_bf16(a, b, c, 0, 0, 0); }
; DI void attn_diff_unit(const Params& p, int li, int b, int h, int qb, char* smem, bool pre, int nh, bool has_next) {
;     ...
;   for (int kt = 0; kt < 32; ++kt) {
;     const char* ks = smem + (kt & 1) * STG; const char* vs = ks + 128 * KR;
; #pragma unroll
;     for (int sub = 0; sub < 2; ++sub) {
;       const int kbase = kt * 128 + sub * 64;
;       const int relmin = kbase - (qb * 128 + 127), relmax = kbase + 63 - qb * 128;
;       const float cb = (relmin >= 128) ? cR : ((relmax <= -128) ? cL : 0.f);
;       f32x16 s0, s1;
; #pragma unroll
;       for (int i = 0; i < 16; ++i) { s0[i] = cb - m; s1[i] = cb - m; }
;       {
;         bf16x8 kf[8];
; #pragma unroll
;         for (int s = 0; s < 4; ++s) {
;           kf[2 * s] = *(const bf16x8*)(ks + (sub * 64 + r32) * KR + (map * 64 + s * 16 + hh * 8) * 2);
;           kf[2 * s + 1] = *(const bf16x8*)(ks + (sub * 64 + 32 + r32) * KR + (map * 64 + s * 16 + hh * 8) * 2);
;         }
;         __builtin_amdgcn_sched_barrier(0); __builtin_amdgcn_s_setprio(1);
; #pragma unroll
;         for (int s = 0; s < 4; ++s) { s0 = mfma32(kf[2 * s], qf[s], s0); s1 = mfma32(kf[2 * s + 1], qf[s], s1); }
;       __builtin_amdgcn_s_setprio(0);
; }
;       if (relmin < 128 && relmax > -128) {
;         const int base = kbase - qpos + 255 + 4 * hh;
; #pragma unroll
;         for (int i = 0; i < 16; ++i) {
;           int i0 = base + (i & 3) + 8 * (i >> 2);
;           int i1 = i0 + 32;
;           i0 = i0 < 0 ? 0 : (i0 > 510 ? 510 : i0);
;           i1 = i1 < 0 ? 0 : (i1 > 510 ? 510 : i1);
;           s0[i] += tab[i0]; s1[i] += tab[i1];
;         }
;       }
.LBB0_568:
	v_add_u32_e32 v174, s45, v254
	ds_read_b128 v[176:179], v174
	ds_read_b128 v[196:199], v174 offset:32
	ds_read_b128 v[200:203], v174 offset:8704
	ds_read_b128 v[204:207], v174 offset:8736
	ds_read_b128 v[208:211], v174 offset:64
	ds_read_b128 v[212:215], v174 offset:96
	ds_read_b128 v[216:219], v174 offset:8768
	ds_read_b128 v[220:223], v174 offset:8800
	s_add_i32 s44, s42, s24
	s_cmp_ge_i32 s44, 0xff
	s_cselect_b64 vcc, -1, 0
	s_cmp_le_i32 s44, 0xffffff41
	s_cselect_b64 s[2:3], -1, 0
	v_cndmask_b32_e64 v64, 0, v156, s[2:3]
	v_cndmask_b32_e32 v64, v64, v157, vcc
	v_sub_f32_e32 v64, v64, v169
	v_mov_b32_e32 v65, v64
	v_mov_b64_e32 v[66:67], v[64:65]
	v_mov_b64_e32 v[68:69], v[64:65]
	v_mov_b64_e32 v[70:71], v[64:65]
	v_mov_b64_e32 v[72:73], v[64:65]
	v_mov_b64_e32 v[74:75], v[64:65]
	v_mov_b64_e32 v[76:77], v[64:65]
	v_mov_b64_e32 v[78:79], v[64:65]
	s_nop 0
	s_waitcnt lgkmcnt(4)
	v_mfma_f32_32x32x16_bf16 v[80:95], v[176:179], v[96:99], v[64:79]
	v_mfma_f32_32x32x16_bf16 v[64:79], v[200:203], v[96:99], v[64:79]
	v_mfma_f32_32x32x16_bf16 v[80:95], v[196:199], v[100:103], v[80:95]
	v_mfma_f32_32x32x16_bf16 v[64:79], v[204:207], v[100:103], v[64:79]
	s_waitcnt lgkmcnt(0)
	v_mfma_f32_32x32x16_bf16 v[80:95], v[208:211], v[104:107], v[80:95]
	v_mfma_f32_32x32x16_bf16 v[64:79], v[216:219], v[104:107], v[64:79]
	v_mfma_f32_32x32x16_bf16 v[80:95], v[212:215], v[108:111], v[80:95]
	v_mfma_f32_32x32x16_bf16 v[64:79], v[220:223], v[108:111], v[64:79]
	s_or_b64 s[2:3], s[2:3], vcc
	s_and_b64 vcc, exec, s[2:3]
	s_cbranch_vccnz .LBB0_570
	v_add_u32_e32 v173, s24, v168
	v_add_u32_e32 v177, 0x100, v173
	s_add_i32 s2, 0, 0x25000
	v_med3_i32 v178, v177, 0, v192
	v_med3_i32 v177, v177, s33, v193
	v_lshl_add_u32 v180, v177, 2, s2
	v_add_u32_e32 v177, 0x101, v173
	v_lshl_add_u32 v179, v178, 2, s2
	v_med3_i32 v178, v177, 0, v192
	v_med3_i32 v177, v177, s33, v193
	v_add_u32_e32 v199, 0x108, v173
	v_add_u32_e32 v175, 0xff, v173
	v_lshl_add_u32 v196, v177, 2, s2
	v_add_u32_e32 v177, 0x102, v173
	v_med3_i32 v200, v199, 0, v192
	v_med3_i32 v199, v199, s33, v193
	v_med3_i32 v176, v175, 0, v192
	v_med3_i32 v175, v175, s33, v193
	v_lshl_add_u32 v181, v178, 2, s2
	v_med3_i32 v178, v177, 0, v192
	v_lshl_add_u32 v202, v199, 2, s2
	v_add_u32_e32 v199, 0x109, v173
	v_lshl_add_u32 v176, v176, 2, s2
	v_lshl_add_u32 v175, v175, 2, s2
	v_med3_i32 v177, v177, s33, v193
	v_lshl_add_u32 v197, v178, 2, s2
	v_lshl_add_u32 v201, v200, 2, s2
	v_med3_i32 v200, v199, 0, v192
	v_med3_i32 v199, v199, s33, v193
	v_add_u32_e32 v207, 0x110, v173
	v_lshl_add_u32 v198, v177, 2, s2
	ds_read_b32 v176, v176
	ds_read_b32 v178, v175 offset:128
	ds_read_b32 v177, v179
	ds_read_b32 v179, v180 offset:128
	ds_read_b32 v180, v181
	ds_read_b32 v196, v196 offset:128
	ds_read_b32 v181, v197
	ds_read_b32 v197, v198 offset:128
	v_add_u32_e32 v175, 0x107, v173
	v_lshl_add_u32 v204, v199, 2, s2
	v_add_u32_e32 v199, 0x10a, v173
	v_med3_i32 v208, v207, 0, v192
	v_med3_i32 v207, v207, s33, v193
	v_med3_i32 v198, v175, 0, v192
	v_med3_i32 v175, v175, s33, v193
	v_lshl_add_u32 v203, v200, 2, s2
	v_med3_i32 v200, v199, 0, v192
	v_lshl_add_u32 v210, v207, 2, s2
	v_add_u32_e32 v207, 0x111, v173
	v_lshl_add_u32 v198, v198, 2, s2
	v_lshl_add_u32 v175, v175, 2, s2
	v_med3_i32 v199, v199, s33, v193
	v_lshl_add_u32 v205, v200, 2, s2
	v_lshl_add_u32 v209, v208, 2, s2
	v_med3_i32 v208, v207, 0, v192
	v_med3_i32 v207, v207, s33, v193
	v_add_u32_e32 v215, 0x118, v173
	v_lshl_add_u32 v206, v199, 2, s2
	ds_read_b32 v198, v198
	ds_read_b32 v200, v175 offset:128
	ds_read_b32 v199, v201
	ds_read_b32 v201, v202 offset:128
	ds_read_b32 v202, v203
	ds_read_b32 v204, v204 offset:128
	ds_read_b32 v203, v205
	ds_read_b32 v205, v206 offset:128
	v_add_u32_e32 v175, 0x10f, v173
	v_lshl_add_u32 v212, v207, 2, s2
	v_add_u32_e32 v207, 0x112, v173
	v_med3_i32 v216, v215, 0, v192
	v_med3_i32 v215, v215, s33, v193
	v_med3_i32 v206, v175, 0, v192
	v_med3_i32 v175, v175, s33, v193
	v_lshl_add_u32 v211, v208, 2, s2
	v_med3_i32 v208, v207, 0, v192
	v_lshl_add_u32 v222, v215, 2, s2
	v_add_u32_e32 v215, 0x119, v173
	v_lshl_add_u32 v206, v206, 2, s2
	v_lshl_add_u32 v175, v175, 2, s2
	v_med3_i32 v207, v207, s33, v193
	v_lshl_add_u32 v213, v208, 2, s2
	v_lshl_add_u32 v217, v216, 2, s2
	v_med3_i32 v216, v215, 0, v192
	v_med3_i32 v215, v215, s33, v193
	v_lshl_add_u32 v214, v207, 2, s2
	ds_read_b32 v206, v206
	ds_read_b32 v208, v175 offset:128
	ds_read_b32 v207, v209
	ds_read_b32 v209, v210 offset:128
	ds_read_b32 v210, v211
	ds_read_b32 v212, v212 offset:128
	ds_read_b32 v211, v213
	ds_read_b32 v213, v214 offset:128
	v_add_u32_e32 v175, 0x117, v173
	v_lshl_add_u32 v220, v215, 2, s2
	v_add_u32_e32 v215, 0x11a, v173
	v_med3_i32 v214, v175, 0, v192
	v_lshl_add_u32 v218, v216, 2, s2
	v_med3_i32 v216, v215, 0, v192
	v_med3_i32 v215, v215, s33, v193
	v_med3_i32 v175, v175, s33, v193
	v_lshl_add_u32 v214, v214, 2, s2
	v_lshl_add_u32 v219, v216, 2, s2
	v_lshl_add_u32 v221, v215, 2, s2
	v_lshl_add_u32 v175, v175, 2, s2
	ds_read_b32 v214, v214
	ds_read_b32 v216, v175 offset:128
	ds_read_b32 v218, v218
	ds_read_b32 v219, v219
	ds_read_b32 v215, v217
	ds_read_b32 v221, v221 offset:128
	ds_read_b32 v220, v220 offset:128
	ds_read_b32 v217, v222 offset:128
	s_waitcnt lgkmcnt(4)
	v_pk_add_f32 v[94:95], v[94:95], v[218:219]
	s_waitcnt lgkmcnt(3)
	v_pk_add_f32 v[92:93], v[92:93], v[214:215]
	v_pk_add_f32 v[90:91], v[90:91], v[210:211]
	v_pk_add_f32 v[88:89], v[88:89], v[206:207]
	v_pk_add_f32 v[86:87], v[86:87], v[202:203]
	v_pk_add_f32 v[84:85], v[84:85], v[198:199]
	v_pk_add_f32 v[82:83], v[82:83], v[180:181]
	v_pk_add_f32 v[80:81], v[80:81], v[176:177]
	s_waitcnt lgkmcnt(1)
	v_pk_add_f32 v[78:79], v[78:79], v[220:221]
	s_waitcnt lgkmcnt(0)
	v_pk_add_f32 v[76:77], v[76:77], v[216:217]
	v_pk_add_f32 v[74:75], v[74:75], v[212:213]
	v_pk_add_f32 v[72:73], v[72:73], v[208:209]
	v_pk_add_f32 v[70:71], v[70:71], v[204:205]
	v_pk_add_f32 v[68:69], v[68:69], v[200:201]
	v_pk_add_f32 v[66:67], v[66:67], v[196:197]
	v_pk_add_f32 v[64:65], v[64:65], v[178:179]

; DI f32x16 mfma32(bf16x8 a, bf16x8 b, f32x16 c) { return __builtin_amdgcn_mfma_f32_32x32x16_bf16(a, b, c, 0, 0, 0); }
; DI bool softmax_tile(f32x16& s0, f32x16& s1, float& m, float& l, float& alpha, bf16x8* pf, int lane, bool first, bool check) {
;   if (first) {
;     float mx = fmaxf(s0[0], s1[0]);
; #pragma unroll
;     for (int i = 1; i < 16; ++i) mx = fmaxf(mx, fmaxf(s0[i], s1[i]));
;     mx = fmaxf(mx, shx(mx, 32, lane));
;     m += mx;
; #pragma unroll
;     for (int i = 0; i < 16; ++i) { s0[i] -= mx; s1[i] -= mx; }
;   }
;   float sum = 0.f;
; #pragma unroll
;   for (int i = 0; i < 16; ++i) { s0[i] = __builtin_amdgcn_exp2f(s0[i]); sum += s0[i]; }
; #pragma unroll
;   for (int i = 0; i < 16; ++i) { s1[i] = __builtin_amdgcn_exp2f(s1[i]); sum += s1[i]; }
;   l += sum;
;   pf[0] = pack8(s0, 0); pf[1] = pack8(s0, 8); pf[2] = pack8(s1, 0); pf[3] = pack8(s1, 8);
;   alpha = 1.f;
;   if (!check) return false;
;   const float rsum = sum + shx(sum, 32, lane);
;   const bool trig = rsum > 65536.f;
;   const bool resc = (__builtin_amdgcn_ballot_w64(trig) != 0ull);
;   alpha = 1.f;
;   if (resc) {
;     const float d = trig ? (float)(__builtin_amdgcn_frexp_expf(rsum) - 7) : 0.f;
;     alpha = __builtin_amdgcn_exp2f(-d);
;     m += d; l *= alpha;
;   }
;   return resc;
; }
; DI void attn_diff_unit(const Params& p, int li, int b, int h, int qb, char* smem, bool pre, int nh, bool has_next) {
;     ...
;     for (int sub = 0; sub < 2; ++sub) {
;       const int kbase = kt * 128 + sub * 64;
;       const int relmin = kbase - (qb * 128 + 127), relmax = kbase + 63 - qb * 128;
;       const float cb = (relmin >= 128) ? cR : ((relmax <= -128) ? cL : 0.f);
;       f32x16 s0, s1;
; #pragma unroll
;       for (int i = 0; i < 16; ++i) { s0[i] = cb - m; s1[i] = cb - m; }
;       {
;         bf16x8 kf[8];
; #pragma unroll
;         for (int s = 0; s < 4; ++s) {
;           kf[2 * s] = *(const bf16x8*)(ks + (sub * 64 + r32) * KR + (map * 64 + s * 16 + hh * 8) * 2);
;           kf[2 * s + 1] = *(const bf16x8*)(ks + (sub * 64 + 32 + r32) * KR + (map * 64 + s * 16 + hh * 8) * 2);
;         }
;         __builtin_amdgcn_sched_barrier(0); __builtin_amdgcn_s_setprio(1);
; #pragma unroll
;         for (int s = 0; s < 4; ++s) { s0 = mfma32(kf[2 * s], qf[s], s0); s1 = mfma32(kf[2 * s + 1], qf[s], s1); }
;       __builtin_amdgcn_s_setprio(0);
; }
.LBB0_572:
	v_add3_u32 v175, s45, v164, v163
	ds_read_b128 v[212:215], v174 offset:17408
	ds_read_b128 v[216:219], v174 offset:26112
	ds_read_b128 v[220:223], v174 offset:17440
	ds_read_b128 v[224:227], v174 offset:26144
	ds_read_b128 v[228:231], v174 offset:17472
	ds_read_b128 v[232:235], v174 offset:26176
	ds_read_b128 v[176:179], v174 offset:17504
	ds_read_b128 v[242:245], v174 offset:26208
	v_add_u32_e32 v236, 0x8800, v175
	v_exp_f32_e32 v80, v80
	v_exp_f32_e32 v81, v81
	v_exp_f32_e32 v82, v82
	v_exp_f32_e32 v83, v83
	v_add_f32_e32 v250, 0, v80
	v_exp_f32_e32 v84, v84
	v_add_f32_e32 v250, v81, v250
	v_exp_f32_e32 v85, v85
	v_add_f32_e32 v250, v82, v250
	v_exp_f32_e32 v86, v86
	v_add_f32_e32 v250, v83, v250
	v_exp_f32_e32 v87, v87
	v_add_f32_e32 v250, v84, v250
	v_exp_f32_e32 v88, v88
	v_add_f32_e32 v250, v85, v250
	v_exp_f32_e32 v89, v89
	v_add_f32_e32 v250, v86, v250
	v_exp_f32_e32 v90, v90
	v_add_f32_e32 v250, v87, v250
	v_exp_f32_e32 v91, v91
	v_add_f32_e32 v250, v88, v250
	v_exp_f32_e32 v92, v92
	v_add_f32_e32 v250, v89, v250
	v_exp_f32_e32 v93, v93
	v_add_f32_e32 v250, v90, v250
	v_exp_f32_e32 v94, v94
	v_add_f32_e32 v250, v91, v250
	v_exp_f32_e32 v95, v95
	v_add_f32_e32 v250, v92, v250
	v_exp_f32_e32 v64, v64
	v_add_f32_e32 v250, v93, v250
	v_exp_f32_e32 v65, v65
	v_add_f32_e32 v250, v94, v250
	v_exp_f32_e32 v66, v66
	v_add_f32_e32 v250, v95, v250
	v_exp_f32_e32 v67, v67
	v_add_f32_e32 v250, v64, v250
	v_exp_f32_e32 v68, v68
	v_add_f32_e32 v250, v65, v250
	v_exp_f32_e32 v69, v69
	v_add_f32_e32 v250, v66, v250
	v_exp_f32_e32 v70, v70
	v_add_f32_e32 v250, v67, v250
	v_exp_f32_e32 v71, v71
	v_add_f32_e32 v250, v68, v250
	v_exp_f32_e32 v72, v72
	v_add_f32_e32 v250, v69, v250
	v_exp_f32_e32 v73, v73
	v_add_f32_e32 v250, v70, v250
	v_exp_f32_e32 v74, v74
	v_add_f32_e32 v250, v71, v250
	v_exp_f32_e32 v75, v75
	v_add_f32_e32 v250, v72, v250
	v_exp_f32_e32 v76, v76
	v_add_f32_e32 v250, v73, v250
	v_exp_f32_e32 v77, v77
	v_add_f32_e32 v250, v74, v250
	v_exp_f32_e32 v78, v78
	v_add_f32_e32 v250, v75, v250
	v_exp_f32_e32 v79, v79
	v_add_f32_e32 v250, v76, v250
	v_add_f32_e32 v250, v77, v250
	v_add_f32_e32 v250, v78, v250
	v_add_f32_e32 v250, v79, v250
	s_and_b32 s2, s43, 3
	v_add_f32_e32 v172, v172, v250
	s_mov_b64 s[46:47], 0
	s_cmp_lg_u32 s2, 0
	s_cbranch_scc1 .Ldp_ck_done
	ds_bpermute_b32 v251, v147, v250
	s_waitcnt lgkmcnt(0)
	v_add_f32_e32 v250, v250, v251
	v_cmp_lt_f32_e32 vcc, s88, v250
	s_cbranch_vccz .Ldp_ck_done
	v_frexp_exp_i32_f32_e32 v251, v250
	v_add_u32_e32 v251, -7, v251
	v_cvt_f32_i32_e32 v251, v251
	s_mov_b64 s[46:47], -1
	v_cndmask_b32_e32 v251, 0, v251, vcc
	v_exp_f32_e64 v252, -v251
	v_add_f32_e32 v169, v169, v251
	v_mul_f32_e32 v172, v172, v252
.Ldp_ck_done:
	v_cvt_pk_bf16_f32 v64, v64, v65
	v_cvt_pk_bf16_f32 v65, v66, v67
	v_cvt_pk_bf16_f32 v66, v68, v69
	v_cvt_pk_bf16_f32 v67, v70, v71
	v_cvt_pk_bf16_f32 v68, v72, v73
	v_cvt_pk_bf16_f32 v69, v74, v75
	v_cvt_pk_bf16_f32 v70, v76, v77
	v_cvt_pk_bf16_f32 v71, v78, v79
	v_cvt_pk_bf16_f32 v72, v80, v81
	v_cvt_pk_bf16_f32 v73, v82, v83
	v_cvt_pk_bf16_f32 v74, v84, v85
	v_cvt_pk_bf16_f32 v75, v86, v87
	v_cvt_pk_bf16_f32 v76, v88, v89
	v_cvt_pk_bf16_f32 v77, v90, v91
	v_cvt_pk_bf16_f32 v78, v92, v93
	v_cvt_pk_bf16_f32 v79, v94, v95
	s_add_i32 s2, s44, 64
	s_cmp_ge_i32 s2, 0xff
	s_cselect_b64 vcc, -1, 0
	s_cmp_le_i32 s2, 0xffffff41
	s_cselect_b64 s[2:3], -1, 0
	v_cndmask_b32_e64 v196, 0, v156, s[2:3]
	v_cndmask_b32_e32 v196, v196, v157, vcc
	v_sub_f32_e32 v196, v196, v169
	v_mov_b32_e32 v197, v196
	v_mov_b64_e32 v[198:199], v[196:197]
	v_mov_b64_e32 v[200:201], v[196:197]
	v_mov_b64_e32 v[202:203], v[196:197]
	v_mov_b64_e32 v[204:205], v[196:197]
	v_mov_b64_e32 v[206:207], v[196:197]
	v_mov_b64_e32 v[208:209], v[196:197]
	v_mov_b64_e32 v[210:211], v[196:197]
	s_waitcnt lgkmcnt(0)
	s_nop 0
	v_mfma_f32_32x32x16_bf16 v[80:95], v[212:215], v[96:99], v[196:211]
	v_mfma_f32_32x32x16_bf16 v[196:211], v[216:219], v[96:99], v[196:211]
	v_mfma_f32_32x32x16_bf16 v[80:95], v[220:223], v[100:103], v[80:95]
	v_mfma_f32_32x32x16_bf16 v[196:211], v[224:227], v[100:103], v[196:211]
	v_mfma_f32_32x32x16_bf16 v[80:95], v[228:231], v[104:107], v[80:95]
	v_mfma_f32_32x32x16_bf16 v[196:211], v[232:235], v[104:107], v[196:211]
	v_mfma_f32_32x32x16_bf16 v[80:95], v[176:179], v[108:111], v[80:95]
	v_mfma_f32_32x32x16_bf16 v[196:211], v[242:245], v[108:111], v[196:211]
	s_or_b64 s[2:3], s[2:3], vcc
	s_and_b64 vcc, exec, s[2:3]
	s_cbranch_vccnz .Ldp_b1_skip
; DI void attn_diff_unit(const Params& p, int li, int b, int h, int qb, char* smem, bool pre, int nh, bool has_next) {
;     ...
;       if (relmin < 128 && relmax > -128) {
;         const int base = kbase - qpos + 255 + 4 * hh;
; #pragma unroll
;         for (int i = 0; i < 16; ++i) {
;           int i0 = base + (i & 3) + 8 * (i >> 2);
;           int i1 = i0 + 32;
;           i0 = i0 < 0 ? 0 : (i0 > 510 ? 510 : i0);
;           i1 = i1 < 0 ? 0 : (i1 > 510 ? 510 : i1);
;           s0[i] += tab[i0]; s1[i] += tab[i1];
;         }
;       }
	s_add_i32 s2, 0, 0x25000
	v_add_u32_e32 v173, s24, v168
	v_add_u32_e32 v212, 0x13f, v173
	v_add_u32_e32 v228, 0x13f, v173
	v_add_u32_e32 v213, 0x140, v173
	v_add_u32_e32 v229, 0x140, v173
	v_add_u32_e32 v214, 0x141, v173
	v_add_u32_e32 v230, 0x141, v173
	v_add_u32_e32 v215, 0x142, v173
	v_add_u32_e32 v231, 0x142, v173
	v_add_u32_e32 v216, 0x147, v173
	v_add_u32_e32 v232, 0x147, v173
	v_add_u32_e32 v217, 0x148, v173
	v_add_u32_e32 v233, 0x148, v173
	v_add_u32_e32 v218, 0x149, v173
	v_add_u32_e32 v234, 0x149, v173
	v_add_u32_e32 v219, 0x14a, v173
	v_add_u32_e32 v235, 0x14a, v173
	v_add_u32_e32 v220, 0x14f, v173
	v_add_u32_e32 v176, 0x14f, v173
	v_add_u32_e32 v221, 0x150, v173
	v_add_u32_e32 v177, 0x150, v173
	v_add_u32_e32 v222, 0x151, v173
	v_add_u32_e32 v178, 0x151, v173
	v_add_u32_e32 v223, 0x152, v173
	v_add_u32_e32 v179, 0x152, v173
	v_add_u32_e32 v224, 0x157, v173
	v_add_u32_e32 v242, 0x157, v173
	v_add_u32_e32 v225, 0x158, v173
	v_add_u32_e32 v243, 0x158, v173
	v_add_u32_e32 v226, 0x159, v173
	v_add_u32_e32 v244, 0x159, v173
	v_add_u32_e32 v227, 0x15a, v173
	v_add_u32_e32 v245, 0x15a, v173
	v_med3_i32 v212, v212, 0, v192
	v_med3_i32 v228, v228, s33, v193
	v_med3_i32 v213, v213, 0, v192
	v_med3_i32 v229, v229, s33, v193
	v_med3_i32 v214, v214, 0, v192
	v_med3_i32 v230, v230, s33, v193
	v_med3_i32 v215, v215, 0, v192
	v_med3_i32 v231, v231, s33, v193
	v_med3_i32 v216, v216, 0, v192
	v_med3_i32 v232, v232, s33, v193
	v_med3_i32 v217, v217, 0, v192
	v_med3_i32 v233, v233, s33, v193
	v_med3_i32 v218, v218, 0, v192
	v_med3_i32 v234, v234, s33, v193
	v_med3_i32 v219, v219, 0, v192
	v_med3_i32 v235, v235, s33, v193
	v_med3_i32 v220, v220, 0, v192
	v_med3_i32 v176, v176, s33, v193
	v_med3_i32 v221, v221, 0, v192
	v_med3_i32 v177, v177, s33, v193
	v_med3_i32 v222, v222, 0, v192
	v_med3_i32 v178, v178, s33, v193
	v_med3_i32 v223, v223, 0, v192
	v_med3_i32 v179, v179, s33, v193
	v_med3_i32 v224, v224, 0, v192
	v_med3_i32 v242, v242, s33, v193
	v_med3_i32 v225, v225, 0, v192
	v_med3_i32 v243, v243, s33, v193
	v_med3_i32 v226, v226, 0, v192
	v_med3_i32 v244, v244, s33, v193
	v_med3_i32 v227, v227, 0, v192
	v_med3_i32 v245, v245, s33, v193
	v_lshl_add_u32 v212, v212, 2, s2
	v_lshl_add_u32 v228, v228, 2, s2
	v_lshl_add_u32 v213, v213, 2, s2
	v_lshl_add_u32 v229, v229, 2, s2
	v_lshl_add_u32 v214, v214, 2, s2
	v_lshl_add_u32 v230, v230, 2, s2
	v_lshl_add_u32 v215, v215, 2, s2
	v_lshl_add_u32 v231, v231, 2, s2
	v_lshl_add_u32 v216, v216, 2, s2
	v_lshl_add_u32 v232, v232, 2, s2
	v_lshl_add_u32 v217, v217, 2, s2
	v_lshl_add_u32 v233, v233, 2, s2
	v_lshl_add_u32 v218, v218, 2, s2
	v_lshl_add_u32 v234, v234, 2, s2
	v_lshl_add_u32 v219, v219, 2, s2
	v_lshl_add_u32 v235, v235, 2, s2
	v_lshl_add_u32 v220, v220, 2, s2
	v_lshl_add_u32 v176, v176, 2, s2
	v_lshl_add_u32 v221, v221, 2, s2
	v_lshl_add_u32 v177, v177, 2, s2
	v_lshl_add_u32 v222, v222, 2, s2
	v_lshl_add_u32 v178, v178, 2, s2
	v_lshl_add_u32 v223, v223, 2, s2
	v_lshl_add_u32 v179, v179, 2, s2
	v_lshl_add_u32 v224, v224, 2, s2
	v_lshl_add_u32 v242, v242, 2, s2
	v_lshl_add_u32 v225, v225, 2, s2
	v_lshl_add_u32 v243, v243, 2, s2
	v_lshl_add_u32 v226, v226, 2, s2
	v_lshl_add_u32 v244, v244, 2, s2
	v_lshl_add_u32 v227, v227, 2, s2
	v_lshl_add_u32 v245, v245, 2, s2
	ds_read_b32 v212, v212
	ds_read_b32 v228, v228 offset:128
	ds_read_b32 v213, v213
	ds_read_b32 v229, v229 offset:128
	ds_read_b32 v214, v214
	ds_read_b32 v230, v230 offset:128
	ds_read_b32 v215, v215
	ds_read_b32 v231, v231 offset:128
	ds_read_b32 v216, v216
	ds_read_b32 v232, v232 offset:128
	ds_read_b32 v217, v217
	ds_read_b32 v233, v233 offset:128
	ds_read_b32 v218, v218
	ds_read_b32 v234, v234 offset:128
	ds_read_b32 v219, v219
	ds_read_b32 v235, v235 offset:128
	ds_read_b32 v220, v220
	ds_read_b32 v176, v176 offset:128
	ds_read_b32 v221, v221
	ds_read_b32 v177, v177 offset:128
	ds_read_b32 v222, v222
	ds_read_b32 v178, v178 offset:128
	ds_read_b32 v223, v223
	ds_read_b32 v179, v179 offset:128
	ds_read_b32 v224, v224
	ds_read_b32 v242, v242 offset:128
	ds_read_b32 v225, v225
	ds_read_b32 v243, v243 offset:128
	ds_read_b32 v226, v226
	ds_read_b32 v244, v244 offset:128
	ds_read_b32 v227, v227
	ds_read_b32 v245, v245 offset:128
	s_waitcnt lgkmcnt(0)
	v_add_f32_e32 v80, v80, v212
	v_add_f32_e32 v196, v196, v228
	v_add_f32_e32 v81, v81, v213
	v_add_f32_e32 v197, v197, v229
	v_add_f32_e32 v82, v82, v214
	v_add_f32_e32 v198, v198, v230
	v_add_f32_e32 v83, v83, v215
	v_add_f32_e32 v199, v199, v231
	v_add_f32_e32 v84, v84, v216
	v_add_f32_e32 v200, v200, v232
	v_add_f32_e32 v85, v85, v217
	v_add_f32_e32 v201, v201, v233
	v_add_f32_e32 v86, v86, v218
	v_add_f32_e32 v202, v202, v234
	v_add_f32_e32 v87, v87, v219
	v_add_f32_e32 v203, v203, v235
	v_add_f32_e32 v88, v88, v220
	v_add_f32_e32 v204, v204, v176
	v_add_f32_e32 v89, v89, v221
	v_add_f32_e32 v205, v205, v177
	v_add_f32_e32 v90, v90, v222
	v_add_f32_e32 v206, v206, v178
	v_add_f32_e32 v91, v91, v223
	v_add_f32_e32 v207, v207, v179
	v_add_f32_e32 v92, v92, v224
	v_add_f32_e32 v208, v208, v242
	v_add_f32_e32 v93, v93, v225
	v_add_f32_e32 v209, v209, v243
	v_add_f32_e32 v94, v94, v226
	v_add_f32_e32 v210, v210, v244
	v_add_f32_e32 v95, v95, v227
	v_add_f32_e32 v211, v211, v245
; DI f32x16 mfma32(bf16x8 a, bf16x8 b, f32x16 c) { return __builtin_amdgcn_mfma_f32_32x32x16_bf16(a, b, c, 0, 0, 0); }
; DI bool softmax_tile(f32x16& s0, f32x16& s1, float& m, float& l, float& alpha, bf16x8* pf, int lane, bool first, bool check) {
;     ...
;   float sum = 0.f;
; #pragma unroll
;   for (int i = 0; i < 16; ++i) { s0[i] = __builtin_amdgcn_exp2f(s0[i]); sum += s0[i]; }
; #pragma unroll
;   for (int i = 0; i < 16; ++i) { s1[i] = __builtin_amdgcn_exp2f(s1[i]); sum += s1[i]; }
;   l += sum;
;   pf[0] = pack8(s0, 0); pf[1] = pack8(s0, 8); pf[2] = pack8(s1, 0); pf[3] = pack8(s1, 8);
; DI void attn_diff_unit(const Params& p, int li, int b, int h, int qb, char* smem, bool pre, int nh, bool has_next) {
;     ...
;       {
;         bf16x8 vf[2][4];
; #pragma unroll
;         for (int j = 0; j < 4; ++j) vf[0][j] = ld_vfrag_tr(vs, vbase, VR, sub * 64, j * 32);
; #pragma unroll
;         for (int s = 0; s < 4; ++s) {
;           if (s < 3) {
; #pragma unroll
;             for (int j = 0; j < 4; ++j) vf[(s + 1) & 1][j] = ld_vfrag_tr(vs, vbase, VR, sub * 64 + 16 * (s + 1), j * 32);
;           }
;           __builtin_amdgcn_sched_barrier(0); __builtin_amdgcn_s_setprio(1);
; #pragma unroll
;           for (int j = 0; j < 4; ++j) O[j] = mfma32(vf[s & 1][j], pf[s], O[j]);
;         __builtin_amdgcn_s_setprio(0);
; }
;       }
.Ldp_b1_skip:
	ds_read_b64_tr_b16 v[212:213], v175 offset:34816
	ds_read_b64_tr_b16 v[214:215], v175 offset:37376
	ds_read_b64_tr_b16 v[216:217], v175 offset:34880
	ds_read_b64_tr_b16 v[218:219], v175 offset:37440
	ds_read_b64_tr_b16 v[220:221], v175 offset:34944
	ds_read_b64_tr_b16 v[222:223], v175 offset:37504
	ds_read_b64_tr_b16 v[224:225], v175 offset:35008
	ds_read_b64_tr_b16 v[226:227], v175 offset:37568
	ds_read_b64_tr_b16 v[228:229], v175 offset:39936
	ds_read_b64_tr_b16 v[230:231], v175 offset:42496
	ds_read_b64_tr_b16 v[232:233], v175 offset:40000
	ds_read_b64_tr_b16 v[234:235], v175 offset:42560
	ds_read_b64_tr_b16 v[176:177], v175 offset:40064
	ds_read_b64_tr_b16 v[178:179], v175 offset:42624
	ds_read_b64_tr_b16 v[242:243], v175 offset:40128
	ds_read_b64_tr_b16 v[244:245], v175 offset:42688
	s_waitcnt lgkmcnt(8)
	v_mfma_f32_32x32x16_bf16 v[48:63], v[212:215], v[72:75], v[48:63]
	v_exp_f32_e32 v80, v80
	v_exp_f32_e32 v81, v81
	v_mfma_f32_32x32x16_bf16 v[32:47], v[216:219], v[72:75], v[32:47]
	v_exp_f32_e32 v82, v82
	v_exp_f32_e32 v83, v83
	v_add_f32_e32 v253, 0, v80
	v_add_f32_e32 v253, v81, v253
	v_mfma_f32_32x32x16_bf16 v[16:31], v[220:223], v[72:75], v[16:31]
	v_exp_f32_e32 v84, v84
	v_exp_f32_e32 v85, v85
	v_add_f32_e32 v253, v82, v253
	v_add_f32_e32 v253, v83, v253
	v_mfma_f32_32x32x16_bf16 v[0:15], v[224:227], v[72:75], v[0:15]
	v_exp_f32_e32 v86, v86
	v_exp_f32_e32 v87, v87
	v_add_f32_e32 v253, v84, v253
	v_add_f32_e32 v253, v85, v253
	ds_read_b64_tr_b16 v[212:213], v175 offset:45056
	ds_read_b64_tr_b16 v[214:215], v175 offset:47616
	ds_read_b64_tr_b16 v[216:217], v175 offset:45120
	ds_read_b64_tr_b16 v[218:219], v175 offset:47680
	ds_read_b64_tr_b16 v[220:221], v175 offset:45184
	ds_read_b64_tr_b16 v[222:223], v175 offset:47744
	ds_read_b64_tr_b16 v[224:225], v175 offset:45248
	ds_read_b64_tr_b16 v[226:227], v175 offset:47808
	s_waitcnt lgkmcnt(8)
	v_mfma_f32_32x32x16_bf16 v[48:63], v[228:231], v[76:79], v[48:63]
	v_exp_f32_e32 v88, v88
	v_exp_f32_e32 v89, v89
	v_add_f32_e32 v253, v86, v253
	v_add_f32_e32 v253, v87, v253
	v_cvt_pk_bf16_f32 v80, v80, v81
	v_mfma_f32_32x32x16_bf16 v[32:47], v[232:235], v[76:79], v[32:47]
	v_exp_f32_e32 v90, v90
	v_exp_f32_e32 v91, v91
	v_add_f32_e32 v253, v88, v253
	v_add_f32_e32 v253, v89, v253
	v_cvt_pk_bf16_f32 v81, v82, v83
	v_mfma_f32_32x32x16_bf16 v[16:31], v[176:179], v[76:79], v[16:31]
	v_exp_f32_e32 v92, v92
	v_exp_f32_e32 v93, v93
	v_add_f32_e32 v253, v90, v253
	v_add_f32_e32 v253, v91, v253
	v_cvt_pk_bf16_f32 v82, v84, v85
	v_mfma_f32_32x32x16_bf16 v[0:15], v[242:245], v[76:79], v[0:15]
	v_exp_f32_e32 v94, v94
	v_exp_f32_e32 v95, v95
	v_add_f32_e32 v253, v92, v253
	v_add_f32_e32 v253, v93, v253
	v_cvt_pk_bf16_f32 v83, v86, v87
	ds_read_b64_tr_b16 v[228:229], v175 offset:50176
	ds_read_b64_tr_b16 v[230:231], v175 offset:52736
	ds_read_b64_tr_b16 v[232:233], v175 offset:50240
	ds_read_b64_tr_b16 v[234:235], v175 offset:52800
	ds_read_b64_tr_b16 v[176:177], v175 offset:50304
	ds_read_b64_tr_b16 v[178:179], v175 offset:52864
	ds_read_b64_tr_b16 v[242:243], v175 offset:50368
	ds_read_b64_tr_b16 v[244:245], v175 offset:52928
	s_waitcnt lgkmcnt(8)
	v_mfma_f32_32x32x16_bf16 v[48:63], v[212:215], v[64:67], v[48:63]
	v_exp_f32_e32 v196, v196
	v_exp_f32_e32 v197, v197
	v_add_f32_e32 v253, v94, v253
	v_add_f32_e32 v253, v95, v253
	v_cvt_pk_bf16_f32 v84, v88, v89
	v_mfma_f32_32x32x16_bf16 v[32:47], v[216:219], v[64:67], v[32:47]
	v_exp_f32_e32 v198, v198
	v_exp_f32_e32 v199, v199
	v_add_f32_e32 v253, v196, v253
	v_add_f32_e32 v253, v197, v253
	v_cvt_pk_bf16_f32 v85, v90, v91
	v_mfma_f32_32x32x16_bf16 v[16:31], v[220:223], v[64:67], v[16:31]
	v_exp_f32_e32 v200, v200
	v_exp_f32_e32 v201, v201
	v_add_f32_e32 v253, v198, v253
	v_add_f32_e32 v253, v199, v253
	v_cvt_pk_bf16_f32 v86, v92, v93
	v_mfma_f32_32x32x16_bf16 v[0:15], v[224:227], v[64:67], v[0:15]
	v_exp_f32_e32 v202, v202
	v_exp_f32_e32 v203, v203
	v_add_f32_e32 v253, v200, v253
	v_add_f32_e32 v253, v201, v253
	v_cvt_pk_bf16_f32 v87, v94, v95
	s_waitcnt lgkmcnt(0)
	v_mfma_f32_32x32x16_bf16 v[48:63], v[228:231], v[68:71], v[48:63]
	v_exp_f32_e32 v204, v204
	v_exp_f32_e32 v205, v205
	v_add_f32_e32 v253, v202, v253
	v_add_f32_e32 v253, v203, v253
	v_cvt_pk_bf16_f32 v196, v196, v197
	v_mfma_f32_32x32x16_bf16 v[32:47], v[232:235], v[68:71], v[32:47]
	v_exp_f32_e32 v206, v206
	v_exp_f32_e32 v207, v207
	v_add_f32_e32 v253, v204, v253
	v_add_f32_e32 v253, v205, v253
	v_cvt_pk_bf16_f32 v197, v198, v199
	v_mfma_f32_32x32x16_bf16 v[16:31], v[176:179], v[68:71], v[16:31]
	v_exp_f32_e32 v208, v208
	v_exp_f32_e32 v209, v209
	v_add_f32_e32 v253, v206, v253
	v_add_f32_e32 v253, v207, v253
	v_cvt_pk_bf16_f32 v198, v200, v201
	v_mfma_f32_32x32x16_bf16 v[0:15], v[242:245], v[68:71], v[0:15]
	v_exp_f32_e32 v210, v210
	v_exp_f32_e32 v211, v211
	v_add_f32_e32 v253, v208, v253
	v_add_f32_e32 v253, v209, v253
	v_cvt_pk_bf16_f32 v199, v202, v203
	v_add_f32_e32 v253, v210, v253
	v_add_f32_e32 v253, v211, v253
	v_cvt_pk_bf16_f32 v200, v204, v205
	v_cvt_pk_bf16_f32 v201, v206, v207
	v_cvt_pk_bf16_f32 v202, v208, v209
	v_cvt_pk_bf16_f32 v203, v210, v211
	v_add_f32_e32 v172, v172, v253
	s_andn2_b64 vcc, exec, s[46:47]
	s_cbranch_vccnz .Ldp_nors
; DI void attn_diff_unit(const Params& p, int li, int b, int h, int qb, char* smem, bool pre, int nh, bool has_next) {
;     ...
;   auto put_stage = [&](char* kb) {
;     char* vb = kb + 128 * KR;
; #pragma unroll
;     for (int i = 0; i < 4; ++i) {
;       *(u32x4*)(kb + (krow + 32 * i) * KR + kpart * 16) = rk[i];
;       *(u32x4*)(vb + (krow + 32 * i) * VR + kpart * 16) = rv[i];
;     }
;   };
;     ...
;       if (resc) {
; #pragma unroll
;         for (int j = 0; j < 4; ++j) scale16(O[j], alpha);
;       }
;     }
;     if (kt + 1 < 32) put_stage(smem + ((kt + 1) & 1) * STG);
;     else if (has_next) put_stage(smem);
;     __syncthreads();
	s_nop 15
	v_mul_f32_e32 v0, v0, v252
	v_mul_f32_e32 v1, v1, v252
	v_mul_f32_e32 v2, v2, v252
	v_mul_f32_e32 v3, v3, v252
	v_mul_f32_e32 v4, v4, v252
	v_mul_f32_e32 v5, v5, v252
	v_mul_f32_e32 v6, v6, v252
	v_mul_f32_e32 v7, v7, v252
	v_mul_f32_e32 v8, v8, v252
	v_mul_f32_e32 v9, v9, v252
	v_mul_f32_e32 v10, v10, v252
	v_mul_f32_e32 v11, v11, v252
	v_mul_f32_e32 v12, v12, v252
	v_mul_f32_e32 v13, v13, v252
	v_mul_f32_e32 v14, v14, v252
	v_mul_f32_e32 v15, v15, v252
	v_mul_f32_e32 v16, v16, v252
	v_mul_f32_e32 v17, v17, v252
	v_mul_f32_e32 v18, v18, v252
	v_mul_f32_e32 v19, v19, v252
	v_mul_f32_e32 v20, v20, v252
	v_mul_f32_e32 v21, v21, v252
	v_mul_f32_e32 v22, v22, v252
	v_mul_f32_e32 v23, v23, v252
	v_mul_f32_e32 v24, v24, v252
	v_mul_f32_e32 v25, v25, v252
	v_mul_f32_e32 v26, v26, v252
	v_mul_f32_e32 v27, v27, v252
	v_mul_f32_e32 v28, v28, v252
	v_mul_f32_e32 v29, v29, v252
	v_mul_f32_e32 v30, v30, v252
	v_mul_f32_e32 v31, v31, v252
	v_mul_f32_e32 v32, v32, v252
	v_mul_f32_e32 v33, v33, v252
	v_mul_f32_e32 v34, v34, v252
	v_mul_f32_e32 v35, v35, v252
	v_mul_f32_e32 v36, v36, v252
	v_mul_f32_e32 v37, v37, v252
	v_mul_f32_e32 v38, v38, v252
	v_mul_f32_e32 v39, v39, v252
	v_mul_f32_e32 v40, v40, v252
	v_mul_f32_e32 v41, v41, v252
	v_mul_f32_e32 v42, v42, v252
	v_mul_f32_e32 v43, v43, v252
	v_mul_f32_e32 v44, v44, v252
	v_mul_f32_e32 v45, v45, v252
	v_mul_f32_e32 v46, v46, v252
	v_mul_f32_e32 v47, v47, v252
	v_mul_f32_e32 v48, v48, v252
	v_mul_f32_e32 v49, v49, v252
	v_mul_f32_e32 v50, v50, v252
	v_mul_f32_e32 v51, v51, v252
	v_mul_f32_e32 v52, v52, v252
	v_mul_f32_e32 v53, v53, v252
	v_mul_f32_e32 v54, v54, v252
	v_mul_f32_e32 v55, v55, v252
	v_mul_f32_e32 v56, v56, v252
	v_mul_f32_e32 v57, v57, v252
	v_mul_f32_e32 v58, v58, v252
	v_mul_f32_e32 v59, v59, v252
	v_mul_f32_e32 v60, v60, v252
	v_mul_f32_e32 v61, v61, v252
	v_mul_f32_e32 v62, v62, v252
	v_mul_f32_e32 v63, v63, v252
.Ldp_nors:
	ds_read_b64_tr_b16 v[212:213], v175 offset:55296
	ds_read_b64_tr_b16 v[214:215], v175 offset:57856
	ds_read_b64_tr_b16 v[216:217], v175 offset:55360
	ds_read_b64_tr_b16 v[218:219], v175 offset:57920
	ds_read_b64_tr_b16 v[220:221], v175 offset:55424
	ds_read_b64_tr_b16 v[222:223], v175 offset:57984
	ds_read_b64_tr_b16 v[224:225], v175 offset:55488
	ds_read_b64_tr_b16 v[226:227], v175 offset:58048
	ds_read_b64_tr_b16 v[228:229], v175 offset:60416
	ds_read_b64_tr_b16 v[230:231], v175 offset:62976
	ds_read_b64_tr_b16 v[232:233], v175 offset:60480
	ds_read_b64_tr_b16 v[234:235], v175 offset:63040
	ds_read_b64_tr_b16 v[176:177], v175 offset:60544
	ds_read_b64_tr_b16 v[178:179], v175 offset:63104
	ds_read_b64_tr_b16 v[242:243], v175 offset:60608
	ds_read_b64_tr_b16 v[244:245], v175 offset:63168
	s_waitcnt lgkmcnt(8)
	v_mfma_f32_32x32x16_bf16 v[48:63], v[212:215], v[80:83], v[48:63]
	v_mfma_f32_32x32x16_bf16 v[32:47], v[216:219], v[80:83], v[32:47]
	v_mfma_f32_32x32x16_bf16 v[16:31], v[220:223], v[80:83], v[16:31]
	v_mfma_f32_32x32x16_bf16 v[0:15], v[224:227], v[80:83], v[0:15]
	ds_read_b64_tr_b16 v[212:213], v236 offset:30720
	ds_read_b64_tr_b16 v[214:215], v236 offset:33280
	ds_read_b64_tr_b16 v[216:217], v236 offset:30784
	ds_read_b64_tr_b16 v[218:219], v236 offset:33344
	ds_read_b64_tr_b16 v[220:221], v236 offset:30848
	ds_read_b64_tr_b16 v[222:223], v236 offset:33408
	ds_read_b64_tr_b16 v[224:225], v236 offset:30912
	ds_read_b64_tr_b16 v[226:227], v236 offset:33472
	s_waitcnt lgkmcnt(8)
	v_mfma_f32_32x32x16_bf16 v[48:63], v[228:231], v[84:87], v[48:63]
	v_mfma_f32_32x32x16_bf16 v[32:47], v[232:235], v[84:87], v[32:47]
	v_mfma_f32_32x32x16_bf16 v[16:31], v[176:179], v[84:87], v[16:31]
	v_mfma_f32_32x32x16_bf16 v[0:15], v[242:245], v[84:87], v[0:15]
	ds_read_b64_tr_b16 v[228:229], v236 offset:35840
	ds_read_b64_tr_b16 v[230:231], v236 offset:38400
	ds_read_b64_tr_b16 v[232:233], v236 offset:35904
	ds_read_b64_tr_b16 v[234:235], v236 offset:38464
	ds_read_b64_tr_b16 v[176:177], v236 offset:35968
	ds_read_b64_tr_b16 v[178:179], v236 offset:38528
	ds_read_b64_tr_b16 v[242:243], v236 offset:36032
	ds_read_b64_tr_b16 v[244:245], v236 offset:38592
	s_waitcnt lgkmcnt(8)
	v_mfma_f32_32x32x16_bf16 v[48:63], v[212:215], v[196:199], v[48:63]
	v_mfma_f32_32x32x16_bf16 v[32:47], v[216:219], v[196:199], v[32:47]
	v_mfma_f32_32x32x16_bf16 v[16:31], v[220:223], v[196:199], v[16:31]
	v_mfma_f32_32x32x16_bf16 v[0:15], v[224:227], v[196:199], v[0:15]
	s_waitcnt lgkmcnt(0)
	v_mfma_f32_32x32x16_bf16 v[48:63], v[228:231], v[200:203], v[48:63]
	v_mfma_f32_32x32x16_bf16 v[32:47], v[232:235], v[200:203], v[32:47]
	v_mfma_f32_32x32x16_bf16 v[16:31], v[176:179], v[200:203], v[16:31]
	v_mfma_f32_32x32x16_bf16 v[0:15], v[242:245], v[200:203], v[0:15]
	s_cmpk_eq_i32 s24, 0xf80
	s_mov_b64 s[2:3], -1
	s_cbranch_scc1 .LBB0_583
	s_xor_b32 s2, s45, 0x12800
	v_add3_u32 v64, s2, v161, v159
	v_add3_u32 v65, s2, v160, v159
	s_mov_b64 s[2:3], 0
	s_waitcnt vmcnt(0)
	ds_write_b128 v64, v[116:119]
	v_add_u32_e32 v66, 0x8800, v65
	ds_write_b128 v65, v[128:131] offset:34816
	ds_write_b128 v64, v[112:115] offset:8704
	ds_write_b128 v65, v[120:123] offset:45056
	ds_write_b128 v64, v[124:127] offset:17408
	ds_write_b128 v65, v[132:135] offset:55296
	ds_write_b128 v64, v[136:139] offset:26112
	ds_write_b128 v66, v[140:143] offset:30720

; DI void attn_diff_unit(const Params& p, int li, int b, int h, int qb, char* smem, bool pre, int nh, bool has_next) {
;     ...
;   auto get_stage = [&](int st) {
;     const int k0 = st * 128;
; #pragma unroll
;     for (int i = 0; i < 4; ++i) { rk[i] = *(const u32x4*)(gk + (size_t)(k0 + i * 32) * 1024); rv[i] = *(const u32x4*)(gv + (size_t)(k0 + i * 32) * 1024); }
;   };
;     ...
;     if (kt + 1 < 32) put_stage(smem + ((kt + 1) & 1) * STG);
;     else if (has_next) put_stage(smem);
;     __syncthreads();
;     if (kt + 2 < 32) get_stage(kt + 2);
;     else if (kt == 30 && has_next) { gk += (nh - h) * 128; gv += (nh - h) * 128; get_stage(0); }
.LBB0_590:
	s_andn2_b64 vcc, exec, s[2:3]
	s_cbranch_vccnz .LBB0_592
	s_add_u32 vcc_lo, s100, 0x4000000
	s_addc_u32 vcc_hi, s101, 0
	global_load_dwordx4 v[112:115], v247, s[100:101]
	global_load_dwordx4 v[120:123], v247, vcc
	global_load_dwordx4 v[124:127], v248, s[100:101]
	global_load_dwordx4 v[132:135], v248, vcc
	global_load_dwordx4 v[116:119], v246, s[100:101]
	global_load_dwordx4 v[136:139], v249, s[100:101]
	global_load_dwordx4 v[128:131], v246, vcc
	global_load_dwordx4 v[140:143], v249, vcc
	s_add_u32 s100, s100, 0x40000
	s_addc_u32 s101, s101, 0
.LBB0_592:
	s_addk_i32 s24, 0x80
	s_cmpk_eq_i32 s24, 0x1000
	s_cbranch_scc1 .LBB0_594
	s_add_i32 s43, s43, 1
	s_xor_b32 s45, s45, 0x12800
	s_branch .LBB0_568

; DI f32x16 mfma32(bf16x8 a, bf16x8 b, f32x16 c) { return __builtin_amdgcn_mfma_f32_32x32x16_bf16(a, b, c, 0, 0, 0); }
; DI void attn_mla_unit(const Params& p, int b, int h, int qb, char* smem, bool pre, int nh, bool has_next) {
;     ...
;     const char* ks = smem + (kt & 1) * STG; const char* vs = ks + 128 * KR;
; #pragma unroll
;     for (int sub = 0; sub < 2; ++sub) {
;       f32x16 s0, s1;
; #pragma unroll
;       for (int i = 0; i < 16; ++i) { s0[i] = -m; s1[i] = -m; }
;       {
;         bf16x8 kf[12];
; #pragma unroll
;         for (int s = 0; s < 6; ++s) {
;           kf[2 * s] = *(const bf16x8*)(ks + (sub * 64 + r32) * KR + (s * 16 + hh * 8) * 2);
;           kf[2 * s + 1] = *(const bf16x8*)(ks + (sub * 64 + 32 + r32) * KR + (s * 16 + hh * 8) * 2);
;         }
;         __builtin_amdgcn_sched_barrier(0); __builtin_amdgcn_s_setprio(1);
; #pragma unroll
;         for (int s = 0; s < 6; ++s) { s0 = mfma32(kf[2 * s], qf[s], s0); s1 = mfma32(kf[2 * s + 1], qf[s], s1); }
;       __builtin_amdgcn_s_setprio(0);
; }
;       float alpha; bf16x8 pf[4];
;       const bool resc = softmax_tile(s0, s1, m, l, alpha, pf, lane, (kt == 0) && (sub == 0), (sub == 0) && ((kt & 3) == 0));
;       {
;         bf16x8 vf[8];
; #pragma unroll
;         for (int s = 0; s < 4; ++s) { vf[2 * s] = ld_vfrag_tr(vs, vbase, VR, sub * 64 + 16 * s, 0); vf[2 * s + 1] = ld_vfrag_tr(vs, vbase, VR, sub * 64 + 16 * s, 32); }
;         __builtin_amdgcn_sched_barrier(0); __builtin_amdgcn_s_setprio(1);
; #pragma unroll
;         for (int s = 0; s < 4; ++s) { O0 = mfma32(vf[2 * s], pf[s], O0); O1 = mfma32(vf[2 * s + 1], pf[s], O1); }
;       __builtin_amdgcn_s_setprio(0);
; }
;       if (resc) { scale16(O0, alpha); scale16(O1, alpha); }
;     }
;     if (kt + 1 < 32) put_stage(smem + ((kt + 1) & 1) * STG);
;     else if (has_next) put_stage(smem);
;     __syncthreads();
;     if (kt + 2 < 32) get_stage(kt + 2);
.LBB0_1489:
	ds_read_b128 v[70:73], v67 offset:13312
	ds_read_b128 v[74:77], v67 offset:13344
	ds_read_b128 v[132:135], v67 offset:19968
	ds_read_b128 v[154:157], v67 offset:20000
	ds_read_b128 v[158:161], v67 offset:13376
	ds_read_b128 v[162:165], v67 offset:13408
	ds_read_b128 v[166:169], v67 offset:20032
	ds_read_b128 v[170:173], v67 offset:20064
	ds_read_b128 v[174:177], v67 offset:13440
	ds_read_b128 v[178:181], v67 offset:13472
	ds_read_b128 v[196:199], v67 offset:20096
	ds_read_b128 v[200:203], v67 offset:20128
	v_xor_b32_e32 v32, 0x80000000, v150
	v_mov_b32_e32 v33, v32
	v_mov_b64_e32 v[34:35], v[32:33]
	v_mov_b64_e32 v[36:37], v[32:33]
	v_mov_b64_e32 v[38:39], v[32:33]
	v_mov_b64_e32 v[40:41], v[32:33]
	v_mov_b64_e32 v[42:43], v[32:33]
	v_mov_b64_e32 v[44:45], v[32:33]
	v_mov_b64_e32 v[46:47], v[32:33]
	s_setprio 1
	s_waitcnt lgkmcnt(8)
	v_mfma_f32_32x32x16_bf16 v[48:63], v[70:73], v[100:103], v[32:47]
	v_mfma_f32_32x32x16_bf16 v[32:47], v[132:135], v[100:103], v[32:47]
	v_mfma_f32_32x32x16_bf16 v[48:63], v[74:77], v[96:99], v[48:63]
	v_mfma_f32_32x32x16_bf16 v[32:47], v[154:157], v[96:99], v[32:47]
	s_waitcnt lgkmcnt(4)
	v_mfma_f32_32x32x16_bf16 v[48:63], v[158:161], v[92:95], v[48:63]
	v_mfma_f32_32x32x16_bf16 v[32:47], v[166:169], v[92:95], v[32:47]
	v_mfma_f32_32x32x16_bf16 v[48:63], v[162:165], v[88:91], v[48:63]
	v_mfma_f32_32x32x16_bf16 v[32:47], v[170:173], v[88:91], v[32:47]
	s_waitcnt lgkmcnt(0)
	v_mfma_f32_32x32x16_bf16 v[48:63], v[174:177], v[84:87], v[48:63]
	v_mfma_f32_32x32x16_bf16 v[32:47], v[196:199], v[84:87], v[32:47]
	v_mfma_f32_32x32x16_bf16 v[48:63], v[178:181], v[80:83], v[48:63]
	v_mfma_f32_32x32x16_bf16 v[32:47], v[200:203], v[80:83], v[32:47]
	s_setprio 0
	ds_read_b64_tr_b16 v[132:133], v68 offset:38912
	ds_read_b64_tr_b16 v[134:135], v68 offset:40448
	ds_read_b64_tr_b16 v[156:157], v68 offset:40512
	ds_read_b64_tr_b16 v[154:155], v68 offset:38976
	ds_read_b64_tr_b16 v[158:159], v68 offset:41984
	ds_read_b64_tr_b16 v[160:161], v68 offset:43520
	ds_read_b64_tr_b16 v[164:165], v68 offset:43584
	ds_read_b64_tr_b16 v[162:163], v68 offset:42048
	ds_read_b64_tr_b16 v[166:167], v68 offset:45056
	ds_read_b64_tr_b16 v[168:169], v68 offset:46592
	ds_read_b64_tr_b16 v[172:173], v68 offset:46656
	ds_read_b64_tr_b16 v[170:171], v68 offset:45120
	ds_read_b64_tr_b16 v[174:175], v68 offset:48128
	ds_read_b64_tr_b16 v[176:177], v68 offset:49664
	ds_read_b64_tr_b16 v[180:181], v68 offset:49728
	ds_read_b64_tr_b16 v[178:179], v68 offset:48192
	v_exp_f32_e32 v40, v40
	v_exp_f32_e32 v41, v41
	v_exp_f32_e32 v42, v42
	v_exp_f32_e32 v43, v43
	v_exp_f32_e32 v44, v44
	v_exp_f32_e32 v45, v45
	v_exp_f32_e32 v46, v46
	v_exp_f32_e32 v47, v47
	v_exp_f32_e32 v48, v48
	v_exp_f32_e32 v49, v49
	v_exp_f32_e32 v50, v50
	v_exp_f32_e32 v51, v51
	v_exp_f32_e32 v52, v52
	v_exp_f32_e32 v53, v53
	v_exp_f32_e32 v54, v54
	v_exp_f32_e32 v55, v55
	v_exp_f32_e32 v56, v56
	v_exp_f32_e32 v57, v57
	v_exp_f32_e32 v58, v58
	v_exp_f32_e32 v59, v59
	v_exp_f32_e32 v60, v60
	v_exp_f32_e32 v61, v61
	v_exp_f32_e32 v62, v62
	v_exp_f32_e32 v63, v63
	v_exp_f32_e32 v67, v32
	v_exp_f32_e32 v69, v33
	v_exp_f32_e32 v70, v34
	v_exp_f32_e32 v71, v35
	v_exp_f32_e32 v36, v36
	v_exp_f32_e32 v37, v37
	v_exp_f32_e32 v38, v38
	v_exp_f32_e32 v39, v39
	v_cvt_pk_bf16_f32 v32, v40, v41
	v_cvt_pk_bf16_f32 v33, v42, v43
	v_cvt_pk_bf16_f32 v34, v44, v45
	v_cvt_pk_bf16_f32 v35, v46, v47
	v_cvt_pk_bf16_f32 v72, v67, v69
	v_cvt_pk_bf16_f32 v73, v70, v71
	v_cvt_pk_bf16_f32 v74, v36, v37
	v_cvt_pk_bf16_f32 v75, v38, v39
	v_cvt_pk_bf16_f32 v76, v56, v57
	v_cvt_pk_bf16_f32 v77, v58, v59
	v_cvt_pk_bf16_f32 v78, v60, v61
	v_cvt_pk_bf16_f32 v79, v62, v63
	v_cvt_pk_bf16_f32 v196, v48, v49
	v_cvt_pk_bf16_f32 v197, v50, v51
	v_cvt_pk_bf16_f32 v198, v52, v53
	v_cvt_pk_bf16_f32 v199, v54, v55
	s_setprio 1
	s_waitcnt lgkmcnt(8)
	v_mfma_f32_32x32x16_bf16 v[16:31], v[132:135], v[196:199], v[16:31]
	v_mfma_f32_32x32x16_bf16 v[0:15], v[154:157], v[196:199], v[0:15]
	v_mfma_f32_32x32x16_bf16 v[16:31], v[158:161], v[76:79], v[16:31]
	v_mfma_f32_32x32x16_bf16 v[0:15], v[162:165], v[76:79], v[0:15]
	s_waitcnt lgkmcnt(0)
	v_mfma_f32_32x32x16_bf16 v[16:31], v[166:169], v[72:75], v[16:31]
	v_mfma_f32_32x32x16_bf16 v[0:15], v[170:173], v[72:75], v[0:15]
	v_mfma_f32_32x32x16_bf16 v[16:31], v[174:177], v[32:35], v[16:31]
	v_mfma_f32_32x32x16_bf16 v[0:15], v[178:181], v[32:35], v[0:15]
	s_setprio 0
	s_bitcmp1_b32 s18, 0
	s_cselect_b32 s16, 0xc800, 0
	s_add_i32 s16, s16, 0
	v_add3_u32 v32, s16, v142, v138
	v_add3_u32 v33, s16, v139, v138
	s_waitcnt vmcnt(0)
	ds_write_b128 v32, v[104:107]
	ds_write_b128 v33, v[108:111] offset:26624
	ds_write_b128 v32, v[112:115] offset:13312
	ds_write_b128 v33, v[116:119] offset:38912
	v_add3_u32 v32, s16, v143, v146
	s_cmp_gt_u32 s19, 29
	s_mov_b64 s[16:17], -1
	ds_write_b128 v32, v[120:123] offset:128
	s_waitcnt lgkmcnt(0)
	s_barrier
	s_cbranch_scc0 .LBB0_1493
	s_cmp_lg_u32 s12, 0x410000
	s_cselect_b64 s[16:17], -1, 0
	s_xor_b64 s[20:21], s[10:11], -1
	s_or_b64 s[16:17], s[20:21], s[16:17]
	s_and_b64 vcc, exec, s[16:17]
	v_mov_b64_e32 v[32:33], v[128:129]
	v_mov_b64_e32 v[34:35], v[130:131]
	s_cbranch_vccnz .LBB0_1492
	v_lshl_add_u64 v[32:33], v[128:129], 0, s[14:15]
	v_add_co_u32_e32 v72, vcc, 0x10000, v32
	v_lshl_add_u64 v[34:35], v[130:131], 0, s[14:15]
	s_nop 0
	v_addc_co_u32_e32 v73, vcc, 0, v33, vcc
	global_load_dwordx4 v[104:107], v[32:33], off
	global_load_dwordx4 v[112:115], v[72:73], off
	v_add_co_u32_e32 v72, vcc, 0x10000, v34
	s_nop 1
	v_addc_co_u32_e32 v73, vcc, 0, v35, vcc
	global_load_dwordx4 v[108:111], v[34:35], off
	global_load_dwordx4 v[116:119], v[72:73], off
	global_load_dwordx4 v[120:123], v[126:127], off

; DI void attn_na_unit(const Params& p, int li, int b, int r, int hp, char* smem) {
;     ...
;   for (int kt = 0; kt < 8; ++kt) {
;     __syncthreads();
; #pragma unroll
;     for (int i = 0; i < 4; ++i) {
;       *(u32x4*)(ks + (krow + 16 * i) * KR + kpart * 16) = rk[i];
;       *(u32x4*)(vs + (krow + 16 * i) * VR + kpart * 16) = rv[i];
;     }
;     __syncthreads();
;     if (kt + 1 < 8) {
;       const int k0 = (kt + 1) * 64;
; #pragma unroll
;       for (int i = 0; i < 4; ++i) { rk[i] = *(const u32x4*)(gk + (size_t)(k0 + i * 16) * 512); rv[i] = *(const u32x4*)(gv + (size_t)(k0 + i * 16) * 512); }
;     }
.LBB0_1539:
	s_cmpk_eq_i32 s9, 0xff84
	s_barrier
	s_waitcnt vmcnt(0)
	ds_write_b128 v144, v[80:83]
	ds_write_b128 v148, v[84:87] offset:17408
	ds_write_b128 v144, v[88:91] offset:4352
	ds_write_b128 v148, v[92:95] offset:22528
	ds_write_b128 v144, v[96:99] offset:8704
	ds_write_b128 v148, v[100:103] offset:27648
	ds_write_b128 v144, v[104:107] offset:13056
	ds_write_b128 v148, v[108:111] offset:32768
	s_waitcnt lgkmcnt(0)
	s_barrier
	s_cbranch_scc1 .LBB0_1541
	v_add_co_u32_e32 v32, vcc, 0xfdff4000, v114
	s_nop 1
	v_addc_co_u32_e32 v33, vcc, -1, v115, vcc
	v_add_co_u32_e32 v34, vcc, 0xffff4000, v114
	s_nop 1
	v_addc_co_u32_e32 v35, vcc, -1, v115, vcc
	global_load_dwordx4 v[80:83], v[32:33], off
	global_load_dwordx4 v[84:87], v[34:35], off
	v_add_co_u32_e32 v32, vcc, 0xfdff8000, v114
	s_nop 1
	v_addc_co_u32_e32 v33, vcc, -1, v115, vcc
	v_add_co_u32_e32 v34, vcc, 0xffff8000, v114
	s_nop 1
	v_addc_co_u32_e32 v35, vcc, -1, v115, vcc
	global_load_dwordx4 v[88:91], v[32:33], off
	global_load_dwordx4 v[92:95], v[34:35], off
	v_add_co_u32_e32 v32, vcc, 0xfdffc000, v114
	s_nop 1
	v_addc_co_u32_e32 v33, vcc, -1, v115, vcc
	v_add_co_u32_e32 v34, vcc, 0xffffc000, v114
	s_nop 1
	v_addc_co_u32_e32 v35, vcc, -1, v115, vcc
	global_load_dwordx4 v[96:99], v[32:33], off
	global_load_dwordx4 v[100:103], v[34:35], off
	v_add_co_u32_e32 v32, vcc, 0xfe000000, v114
	s_nop 1
	v_addc_co_u32_e32 v33, vcc, -1, v115, vcc
	global_load_dwordx4 v[104:107], v[32:33], off
	global_load_dwordx4 v[108:111], v[114:115], off
